# ssd full-loop rewrite (lean barrier, mid-loop staging, transposed xdt/a layout) with lo-half selects only
# baseline (speedup 1.0000x reference)
; __device__ __forceinline__ void ssd_scan_unit(CP p, int l, int u, char* smem) {
;     ...
;     for (int s = 0; s < 16; ++s) {
;       const float* sb = cb + (s + 1) * SST;
;       const float4 B0n = *reinterpret_cast<const float4*>(sb + j * 4), B1n = *reinterpret_cast<const float4*>(sb + 64 + j * 4);
;       const float4 C0n = *reinterpret_cast<const float4*>(sb + 128 + j * 4), C1n = *reinterpret_cast<const float4*>(sb + 192 + j * 4);
;       const float xdtn = sb[256 + prow], xrn = sb[272 + prow], an = sb[288];
;       __builtin_amdgcn_sched_barrier(0);
;       hs[0] = fmaf(a, hs[0], xdt * B0.x); hs[1] = fmaf(a, hs[1], xdt * B0.y); hs[2] = fmaf(a, hs[2], xdt * B0.z); hs[3] = fmaf(a, hs[3], xdt * B0.w);
;       hs[4] = fmaf(a, hs[4], xdt * B1.x); hs[5] = fmaf(a, hs[5], xdt * B1.y); hs[6] = fmaf(a, hs[6], xdt * B1.z); hs[7] = fmaf(a, hs[7], xdt * B1.w);
;       float y = hs[0] * C0.x + hs[1] * C0.y + hs[2] * C0.z + hs[3] * C0.w + hs[4] * C1.x + hs[5] * C1.y + hs[6] * C1.z + hs[7] * C1.w;
;       y = allreduce16(y);
;       y = fmaf(Dh, xr, y);
;       if (j == s) ykeep = y;
;       B0 = B0n; B1 = B1n; C0 = C0n; C1 = C1n; xdt = xdtn; xr = xrn; a = an;
;     }
.Lsd_head:
	s_add_i32 s28, s4, 1
	s_bitcmp1_b32 s4, 0
	s_cselect_b32 s12, 0x4a00, 0
	s_cselect_b32 s13, 0x40, 0
	s_add_i32 s12, s63, s12
	s_add_i32 s13, s63, s13
	v_lshl_add_u32 v84, v56, 2, s12
	v_add_u32_e32 v85, s12, v82
	v_mov_b32_e32 v86, s13
	v_add_u32_e32 v87, s12, v81
	ds_read_b128 v[106:109], v85 offset:1024
	ds_read_b128 v[134:137], v86 offset:37888
	ds_read_b128 v[90:93], v84 offset:0
	ds_read_b128 v[94:97], v84 offset:256
	ds_read_b128 v[98:101], v84 offset:512
	ds_read_b128 v[102:105], v84 offset:768
	ds_read_b128 v[112:115], v84 offset:1184
	ds_read_b128 v[116:119], v84 offset:1440
	ds_read_b128 v[120:123], v84 offset:1696
	ds_read_b128 v[124:127], v84 offset:1952
	ds_read_b32 v186, v87 offset:1088
	s_waitcnt lgkmcnt(7)
	v_pk_mul_f32 v[176:177], v[90:91], v[106:107] op_sel_hi:[1,0]
	v_pk_mul_f32 v[178:179], v[92:93], v[106:107] op_sel_hi:[1,0]
	v_pk_mul_f32 v[180:181], v[94:95], v[106:107] op_sel_hi:[1,0]
	v_pk_mul_f32 v[182:183], v[96:97], v[106:107] op_sel_hi:[1,0]
	ds_read_b128 v[90:93], v84 offset:2368
	ds_read_b128 v[94:97], v84 offset:2624
	s_waitcnt lgkmcnt(5)
	v_pk_fma_f32 v[32:33], v[134:135], v[32:33], v[176:177] op_sel_hi:[0,1,1]
	v_pk_fma_f32 v[38:39], v[134:135], v[38:39], v[178:179] op_sel_hi:[0,1,1]
	v_pk_fma_f32 v[36:37], v[134:135], v[36:37], v[180:181] op_sel_hi:[0,1,1]
	v_pk_fma_f32 v[34:35], v[134:135], v[34:35], v[182:183] op_sel_hi:[0,1,1]
	v_mov_b32_e32 v142, v107
	v_pk_mul_f32 v[184:185], v[32:33], v[98:99]
	v_pk_mul_f32 v[176:177], v[112:113], v[142:143] op_sel_hi:[1,0]
	v_pk_fma_f32 v[184:185], v[38:39], v[100:101], v[184:185]
	v_pk_mul_f32 v[178:179], v[114:115], v[142:143] op_sel_hi:[1,0]
	v_pk_fma_f32 v[184:185], v[36:37], v[102:103], v[184:185]
	v_pk_mul_f32 v[180:181], v[116:117], v[142:143] op_sel_hi:[1,0]
	v_pk_fma_f32 v[184:185], v[34:35], v[104:105], v[184:185]
	v_pk_mul_f32 v[182:183], v[118:119], v[142:143] op_sel_hi:[1,0]
	v_add_f32_e32 v160, v184, v185
	ds_read_b128 v[112:115], v84 offset:3552
	ds_read_b128 v[116:119], v84 offset:3808
	ds_read_b128 v[98:101], v84 offset:2880
	ds_read_b128 v[102:105], v84 offset:3136
	ds_read_b128 v[128:131], v85 offset:1040
	ds_read_b128 v[138:141], v86 offset:37904
	s_waitcnt lgkmcnt(6)
	v_mov_b32_e32 v144, v135
	v_pk_fma_f32 v[32:33], v[144:145], v[32:33], v[176:177] op_sel_hi:[0,1,1]
	v_pk_fma_f32 v[38:39], v[144:145], v[38:39], v[178:179] op_sel_hi:[0,1,1]
	v_pk_fma_f32 v[36:37], v[144:145], v[36:37], v[180:181] op_sel_hi:[0,1,1]
	v_pk_fma_f32 v[34:35], v[144:145], v[34:35], v[182:183] op_sel_hi:[0,1,1]
	v_pk_mul_f32 v[184:185], v[32:33], v[120:121]
	v_pk_mul_f32 v[176:177], v[90:91], v[108:109] op_sel_hi:[1,0]
	v_pk_fma_f32 v[184:185], v[38:39], v[122:123], v[184:185]
	v_pk_mul_f32 v[178:179], v[92:93], v[108:109] op_sel_hi:[1,0]
	v_pk_fma_f32 v[184:185], v[36:37], v[124:125], v[184:185]
	v_pk_mul_f32 v[180:181], v[94:95], v[108:109] op_sel_hi:[1,0]
	v_pk_fma_f32 v[184:185], v[34:35], v[126:127], v[184:185]
	v_pk_mul_f32 v[182:183], v[96:97], v[108:109] op_sel_hi:[1,0]
	v_add_f32_e32 v161, v184, v185
	ds_read_b128 v[90:93], v84 offset:4736
	ds_read_b128 v[94:97], v84 offset:4992
	ds_read_b128 v[120:123], v84 offset:4064
	ds_read_b128 v[124:127], v84 offset:4320
	s_waitcnt lgkmcnt(6)
	v_pk_fma_f32 v[32:33], v[136:137], v[32:33], v[176:177] op_sel_hi:[0,1,1]
	v_pk_fma_f32 v[38:39], v[136:137], v[38:39], v[178:179] op_sel_hi:[0,1,1]
	v_pk_fma_f32 v[36:37], v[136:137], v[36:37], v[180:181] op_sel_hi:[0,1,1]
	v_pk_fma_f32 v[34:35], v[136:137], v[34:35], v[182:183] op_sel_hi:[0,1,1]
	v_mov_b32_e32 v142, v109
	v_pk_mul_f32 v[184:185], v[32:33], v[98:99]
	v_pk_mul_f32 v[176:177], v[112:113], v[142:143] op_sel_hi:[1,0]
	v_pk_fma_f32 v[184:185], v[38:39], v[100:101], v[184:185]
	v_pk_mul_f32 v[178:179], v[114:115], v[142:143] op_sel_hi:[1,0]
	v_pk_fma_f32 v[184:185], v[36:37], v[102:103], v[184:185]
	v_pk_mul_f32 v[180:181], v[116:117], v[142:143] op_sel_hi:[1,0]
	v_pk_fma_f32 v[184:185], v[34:35], v[104:105], v[184:185]
	v_pk_mul_f32 v[182:183], v[118:119], v[142:143] op_sel_hi:[1,0]
	v_add_f32_e32 v162, v184, v185
	ds_read_b128 v[112:115], v84 offset:5920
	ds_read_b128 v[116:119], v84 offset:6176
	ds_read_b128 v[98:101], v84 offset:5248
	ds_read_b128 v[102:105], v84 offset:5504
	s_waitcnt lgkmcnt(4)
	v_mov_b32_e32 v144, v137
	v_pk_fma_f32 v[32:33], v[144:145], v[32:33], v[176:177] op_sel_hi:[0,1,1]
	v_pk_fma_f32 v[38:39], v[144:145], v[38:39], v[178:179] op_sel_hi:[0,1,1]
	v_pk_fma_f32 v[36:37], v[144:145], v[36:37], v[180:181] op_sel_hi:[0,1,1]
	v_pk_fma_f32 v[34:35], v[144:145], v[34:35], v[182:183] op_sel_hi:[0,1,1]
	v_pk_mul_f32 v[184:185], v[32:33], v[120:121]
	v_pk_mul_f32 v[176:177], v[90:91], v[128:129] op_sel_hi:[1,0]
	v_pk_fma_f32 v[184:185], v[38:39], v[122:123], v[184:185]
	v_pk_mul_f32 v[178:179], v[92:93], v[128:129] op_sel_hi:[1,0]
	v_pk_fma_f32 v[184:185], v[36:37], v[124:125], v[184:185]
	v_pk_mul_f32 v[180:181], v[94:95], v[128:129] op_sel_hi:[1,0]
	v_pk_fma_f32 v[184:185], v[34:35], v[126:127], v[184:185]
	v_pk_mul_f32 v[182:183], v[96:97], v[128:129] op_sel_hi:[1,0]
	v_add_f32_e32 v163, v184, v185
	ds_read_b128 v[90:93], v84 offset:7104
	ds_read_b128 v[94:97], v84 offset:7360
	ds_read_b128 v[120:123], v84 offset:6432
	ds_read_b128 v[124:127], v84 offset:6688
	s_waitcnt lgkmcnt(4)
; __device__ __forceinline__ void ssd_scan_unit(CP p, int l, int u, char* smem) {
;     ...
;   auto gload = [&](int c) {
;     const int rb = rowof(b, c * 16);
; #pragma unroll
;     for (int x = 0; x < 2; ++x) {
;       const int e = tid + x * 256, tok = e >> 5, rem = e & 31, which = rem >> 4, part = rem & 15;
;       st[x] = *reinterpret_cast<const uint4*>(SS + (size_t)(rb + tok) * 768 + 256 + which * 256 + g * 128 + part * 8);
;     }
;     {
;       const int tok = tid >> 4, pp = tid & 15;
;       stxr = SS[(size_t)(rb + tok) * 768 + h * 64 + q * 16 + pp];
;       stdt = SD[(size_t)(rb + tok) * 4 + h];
;     }
;   };
;   auto lwrite = [&](int bi) {
; #pragma unroll
;     for (int x = 0; x < 2; ++x) {
;       const int e = tid + x * 256, tok = e >> 5, rem = e & 31, which = rem >> 4, part = rem & 15;
;       float* d = buf + bi * 16 * SST + tok * SST + which * 128 + part * 8;
;       *reinterpret_cast<float4*>(d) = make_float4(lo2f(st[x].x), hi2f(st[x].x), lo2f(st[x].y), hi2f(st[x].y));
;       *reinterpret_cast<float4*>(d + 4) = make_float4(lo2f(st[x].z), hi2f(st[x].z), lo2f(st[x].w), hi2f(st[x].w));
;     }
;     {
;       const int tok = tid >> 4, pp = tid & 15;
;       float* d = buf + bi * 16 * SST + tok * SST;
;       const float stx = bf2f(stxr);
;       d[256 + pp] = stx * stdt;
;     ...
;     for (int s = 0; s < 16; ++s) {
;       const float* sb = cb + (s + 1) * SST;
;       const float4 B0n = *reinterpret_cast<const float4*>(sb + j * 4), B1n = *reinterpret_cast<const float4*>(sb + 64 + j * 4);
;       const float4 C0n = *reinterpret_cast<const float4*>(sb + 128 + j * 4), C1n = *reinterpret_cast<const float4*>(sb + 192 + j * 4);
;       const float xdtn = sb[256 + prow], xrn = sb[272 + prow], an = sb[288];
;       __builtin_amdgcn_sched_barrier(0);
;       hs[0] = fmaf(a, hs[0], xdt * B0.x); hs[1] = fmaf(a, hs[1], xdt * B0.y); hs[2] = fmaf(a, hs[2], xdt * B0.z); hs[3] = fmaf(a, hs[3], xdt * B0.w);
;       hs[4] = fmaf(a, hs[4], xdt * B1.x); hs[5] = fmaf(a, hs[5], xdt * B1.y); hs[6] = fmaf(a, hs[6], xdt * B1.z); hs[7] = fmaf(a, hs[7], xdt * B1.w);
;       float y = hs[0] * C0.x + hs[1] * C0.y + hs[2] * C0.z + hs[3] * C0.w + hs[4] * C1.x + hs[5] * C1.y + hs[6] * C1.z + hs[7] * C1.w;
;       y = allreduce16(y);
;       y = fmaf(Dh, xr, y);
;       if (j == s) ykeep = y;
;       B0 = B0n; B1 = B1n; C0 = C0n; C1 = C1n; xdt = xdtn; xr = xrn; a = an;
;     }
	v_pk_fma_f32 v[32:33], v[138:139], v[32:33], v[176:177] op_sel_hi:[0,1,1]
	v_pk_fma_f32 v[38:39], v[138:139], v[38:39], v[178:179] op_sel_hi:[0,1,1]
	v_pk_fma_f32 v[36:37], v[138:139], v[36:37], v[180:181] op_sel_hi:[0,1,1]
	v_pk_fma_f32 v[34:35], v[138:139], v[34:35], v[182:183] op_sel_hi:[0,1,1]
	v_mov_b32_e32 v142, v129
	v_pk_mul_f32 v[184:185], v[32:33], v[98:99]
	v_pk_mul_f32 v[176:177], v[112:113], v[142:143] op_sel_hi:[1,0]
	v_pk_fma_f32 v[184:185], v[38:39], v[100:101], v[184:185]
	v_pk_mul_f32 v[178:179], v[114:115], v[142:143] op_sel_hi:[1,0]
	v_pk_fma_f32 v[184:185], v[36:37], v[102:103], v[184:185]
	v_pk_mul_f32 v[180:181], v[116:117], v[142:143] op_sel_hi:[1,0]
	v_pk_fma_f32 v[184:185], v[34:35], v[104:105], v[184:185]
	v_pk_mul_f32 v[182:183], v[118:119], v[142:143] op_sel_hi:[1,0]
	v_add_f32_e32 v164, v184, v185
	ds_read_b128 v[112:115], v84 offset:8288
	ds_read_b128 v[116:119], v84 offset:8544
	ds_read_b128 v[98:101], v84 offset:7616
	ds_read_b128 v[102:105], v84 offset:7872
	ds_read_b128 v[106:109], v85 offset:1056
	ds_read_b128 v[134:137], v86 offset:37920
	s_waitcnt lgkmcnt(6)
	v_mov_b32_e32 v144, v139
	v_pk_fma_f32 v[32:33], v[144:145], v[32:33], v[176:177] op_sel_hi:[0,1,1]
	v_pk_fma_f32 v[38:39], v[144:145], v[38:39], v[178:179] op_sel_hi:[0,1,1]
	v_pk_fma_f32 v[36:37], v[144:145], v[36:37], v[180:181] op_sel_hi:[0,1,1]
	v_pk_fma_f32 v[34:35], v[144:145], v[34:35], v[182:183] op_sel_hi:[0,1,1]
	v_pk_mul_f32 v[184:185], v[32:33], v[120:121]
	v_pk_mul_f32 v[176:177], v[90:91], v[130:131] op_sel_hi:[1,0]
	v_pk_fma_f32 v[184:185], v[38:39], v[122:123], v[184:185]
	v_pk_mul_f32 v[178:179], v[92:93], v[130:131] op_sel_hi:[1,0]
	v_pk_fma_f32 v[184:185], v[36:37], v[124:125], v[184:185]
	v_pk_mul_f32 v[180:181], v[94:95], v[130:131] op_sel_hi:[1,0]
	v_pk_fma_f32 v[184:185], v[34:35], v[126:127], v[184:185]
	v_pk_mul_f32 v[182:183], v[96:97], v[130:131] op_sel_hi:[1,0]
	v_add_f32_e32 v165, v184, v185
	ds_read_b128 v[90:93], v84 offset:9472
	ds_read_b128 v[94:97], v84 offset:9728
	ds_read_b128 v[120:123], v84 offset:8800
	ds_read_b128 v[124:127], v84 offset:9056
	s_waitcnt lgkmcnt(6)
	v_pk_fma_f32 v[32:33], v[140:141], v[32:33], v[176:177] op_sel_hi:[0,1,1]
	v_pk_fma_f32 v[38:39], v[140:141], v[38:39], v[178:179] op_sel_hi:[0,1,1]
	v_pk_fma_f32 v[36:37], v[140:141], v[36:37], v[180:181] op_sel_hi:[0,1,1]
	v_pk_fma_f32 v[34:35], v[140:141], v[34:35], v[182:183] op_sel_hi:[0,1,1]
	v_mov_b32_e32 v142, v131
	v_pk_mul_f32 v[184:185], v[32:33], v[98:99]
	v_pk_mul_f32 v[176:177], v[112:113], v[142:143] op_sel_hi:[1,0]
	v_pk_fma_f32 v[184:185], v[38:39], v[100:101], v[184:185]
	v_pk_mul_f32 v[178:179], v[114:115], v[142:143] op_sel_hi:[1,0]
	v_pk_fma_f32 v[184:185], v[36:37], v[102:103], v[184:185]
	v_pk_mul_f32 v[180:181], v[116:117], v[142:143] op_sel_hi:[1,0]
	v_pk_fma_f32 v[184:185], v[34:35], v[104:105], v[184:185]
	v_pk_mul_f32 v[182:183], v[118:119], v[142:143] op_sel_hi:[1,0]
	v_add_f32_e32 v166, v184, v185
	ds_read_b128 v[112:115], v84 offset:10656
	ds_read_b128 v[116:119], v84 offset:10912
	ds_read_b128 v[98:101], v84 offset:9984
	ds_read_b128 v[102:105], v84 offset:10240
	s_waitcnt lgkmcnt(4)
	v_mov_b32_e32 v144, v141
	v_pk_fma_f32 v[32:33], v[144:145], v[32:33], v[176:177] op_sel_hi:[0,1,1]
	v_pk_fma_f32 v[38:39], v[144:145], v[38:39], v[178:179] op_sel_hi:[0,1,1]
	v_pk_fma_f32 v[36:37], v[144:145], v[36:37], v[180:181] op_sel_hi:[0,1,1]
	v_pk_fma_f32 v[34:35], v[144:145], v[34:35], v[182:183] op_sel_hi:[0,1,1]
	v_pk_mul_f32 v[184:185], v[32:33], v[120:121]
	v_pk_mul_f32 v[176:177], v[90:91], v[106:107] op_sel_hi:[1,0]
	v_pk_fma_f32 v[184:185], v[38:39], v[122:123], v[184:185]
	v_pk_mul_f32 v[178:179], v[92:93], v[106:107] op_sel_hi:[1,0]
	v_pk_fma_f32 v[184:185], v[36:37], v[124:125], v[184:185]
	v_pk_mul_f32 v[180:181], v[94:95], v[106:107] op_sel_hi:[1,0]
	v_pk_fma_f32 v[184:185], v[34:35], v[126:127], v[184:185]
	v_pk_mul_f32 v[182:183], v[96:97], v[106:107] op_sel_hi:[1,0]
	v_add_f32_e32 v167, v184, v185
	ds_read_b128 v[90:93], v84 offset:11840
	ds_read_b128 v[94:97], v84 offset:12096
	ds_read_b128 v[120:123], v84 offset:11168
	ds_read_b128 v[124:127], v84 offset:11424
	s_waitcnt vmcnt(0)
	s_bitcmp1_b32 s28, 0
	s_cselect_b32 s2, 0x4a00, 0
	s_cselect_b32 s5, 0x40, 0
	s_add_i32 s2, s63, s2
	v_lshl_add_u32 v8, v50, 2, s2
	v_add3_u32 v18, v8, v51, v52
	v_lshlrev_b32_e32 v12, 16, v0
	v_and_b32_e32 v13, 0xffff0000, v0
	v_lshlrev_b32_e32 v14, 16, v1
	v_and_b32_e32 v15, 0xffff0000, v1
	ds_write_b128 v18, v[12:15]
	v_lshlrev_b32_e32 v12, 16, v2
	v_and_b32_e32 v13, 0xffff0000, v2
	v_lshlrev_b32_e32 v14, 16, v3
	v_and_b32_e32 v15, 0xffff0000, v3
	ds_write_b128 v18, v[12:15] offset:16
	v_lshl_add_u32 v8, v53, 2, s2
	v_add3_u32 v18, v8, v51, v52
	v_lshlrev_b32_e32 v12, 16, v4
	v_and_b32_e32 v13, 0xffff0000, v4
	v_lshlrev_b32_e32 v14, 16, v5
	v_and_b32_e32 v15, 0xffff0000, v5
	ds_write_b128 v18, v[12:15]
	v_lshlrev_b32_e32 v12, 16, v6
	v_and_b32_e32 v13, 0xffff0000, v6
	v_lshlrev_b32_e32 v14, 16, v7
	v_and_b32_e32 v15, 0xffff0000, v7
	ds_write_b128 v18, v[12:15] offset:16
	v_lshlrev_b32_e32 v9, 16, v49
	v_mul_f32_e32 v10, v54, v9
	v_add_u32_e32 v11, s2, v83
	ds_write2_b32 v11, v10, v9 offset1:16
	v_mul_f32_e32 v9, v54, v46
	v_mul_f32_e32 v9, 0xbfb8aa3b, v9
	v_exp_f32_e32 v9, v9
	v_lshl_add_u32 v8, v45, 2, s63
	v_add_u32_e32 v8, s5, v8
	ds_write_b32 v8, v9 offset:37888
	s_cmpk_gt_i32 s4, 0x7e
	s_cbranch_scc1 .Lsd_skipgl
	s_add_i32 s5, s4, 2
	s_lshl_b32 s5, s5, 4
	s_add_i32 s5, s5, s11
	v_add_u32_e32 v8, s5, v45
	v_add_u32_e32 v0, s5, v47
	v_add_u32_e32 v4, s5, v48
	v_ashrrev_i32_e32 v9, 31, v8
	v_mad_i64_i32 v[0:1], s[12:13], v0, s0, v[30:31]
	v_mad_i64_i32 v[4:5], s[12:13], v4, s0, v[30:31]
	v_mad_i64_i32 v[10:11], s[12:13], v8, s0, v[26:27]
	v_lshl_add_u64 v[8:9], v[8:9], 4, s[40:41]
	global_load_dwordx4 v[0:3], v[0:1], off offset:512
	global_load_dwordx4 v[4:7], v[4:5], off offset:512
	global_load_ushort v49, v[10:11], off
	global_load_dword v54, v[8:9], off
; __device__ __forceinline__ void ssd_scan_unit(CP p, int l, int u, char* smem) {
;     ...
;     for (int s = 0; s < 16; ++s) {
;       const float* sb = cb + (s + 1) * SST;
;       const float4 B0n = *reinterpret_cast<const float4*>(sb + j * 4), B1n = *reinterpret_cast<const float4*>(sb + 64 + j * 4);
;       const float4 C0n = *reinterpret_cast<const float4*>(sb + 128 + j * 4), C1n = *reinterpret_cast<const float4*>(sb + 192 + j * 4);
;       const float xdtn = sb[256 + prow], xrn = sb[272 + prow], an = sb[288];
;       __builtin_amdgcn_sched_barrier(0);
;       hs[0] = fmaf(a, hs[0], xdt * B0.x); hs[1] = fmaf(a, hs[1], xdt * B0.y); hs[2] = fmaf(a, hs[2], xdt * B0.z); hs[3] = fmaf(a, hs[3], xdt * B0.w);
;       hs[4] = fmaf(a, hs[4], xdt * B1.x); hs[5] = fmaf(a, hs[5], xdt * B1.y); hs[6] = fmaf(a, hs[6], xdt * B1.z); hs[7] = fmaf(a, hs[7], xdt * B1.w);
;       float y = hs[0] * C0.x + hs[1] * C0.y + hs[2] * C0.z + hs[3] * C0.w + hs[4] * C1.x + hs[5] * C1.y + hs[6] * C1.z + hs[7] * C1.w;
;       y = allreduce16(y);
;       y = fmaf(Dh, xr, y);
;       if (j == s) ykeep = y;
;       B0 = B0n; B1 = B1n; C0 = C0n; C1 = C1n; xdt = xdtn; xr = xrn; a = an;
;     }
.Lsd_skipgl:
	s_waitcnt lgkmcnt(10)
	v_pk_fma_f32 v[32:33], v[134:135], v[32:33], v[176:177] op_sel_hi:[0,1,1]
	v_pk_fma_f32 v[38:39], v[134:135], v[38:39], v[178:179] op_sel_hi:[0,1,1]
	v_pk_fma_f32 v[36:37], v[134:135], v[36:37], v[180:181] op_sel_hi:[0,1,1]
	v_pk_fma_f32 v[34:35], v[134:135], v[34:35], v[182:183] op_sel_hi:[0,1,1]
	v_mov_b32_e32 v142, v107
	v_pk_mul_f32 v[184:185], v[32:33], v[98:99]
	v_pk_mul_f32 v[176:177], v[112:113], v[142:143] op_sel_hi:[1,0]
	v_pk_fma_f32 v[184:185], v[38:39], v[100:101], v[184:185]
	v_pk_mul_f32 v[178:179], v[114:115], v[142:143] op_sel_hi:[1,0]
	v_pk_fma_f32 v[184:185], v[36:37], v[102:103], v[184:185]
	v_pk_mul_f32 v[180:181], v[116:117], v[142:143] op_sel_hi:[1,0]
	v_pk_fma_f32 v[184:185], v[34:35], v[104:105], v[184:185]
	v_pk_mul_f32 v[182:183], v[118:119], v[142:143] op_sel_hi:[1,0]
	v_add_f32_e32 v168, v184, v185
	ds_read_b128 v[112:115], v84 offset:13024
	ds_read_b128 v[116:119], v84 offset:13280
	ds_read_b128 v[98:101], v84 offset:12352
	ds_read_b128 v[102:105], v84 offset:12608
	ds_read_b128 v[128:131], v85 offset:1072
	ds_read_b128 v[138:141], v86 offset:37936
	s_waitcnt lgkmcnt(12)
	v_mov_b32_e32 v144, v135
	v_pk_fma_f32 v[32:33], v[144:145], v[32:33], v[176:177] op_sel_hi:[0,1,1]
	v_pk_fma_f32 v[38:39], v[144:145], v[38:39], v[178:179] op_sel_hi:[0,1,1]
	v_pk_fma_f32 v[36:37], v[144:145], v[36:37], v[180:181] op_sel_hi:[0,1,1]
	v_pk_fma_f32 v[34:35], v[144:145], v[34:35], v[182:183] op_sel_hi:[0,1,1]
	v_pk_mul_f32 v[184:185], v[32:33], v[120:121]
	v_pk_mul_f32 v[176:177], v[90:91], v[108:109] op_sel_hi:[1,0]
	v_pk_fma_f32 v[184:185], v[38:39], v[122:123], v[184:185]
	v_pk_mul_f32 v[178:179], v[92:93], v[108:109] op_sel_hi:[1,0]
	v_pk_fma_f32 v[184:185], v[36:37], v[124:125], v[184:185]
	v_pk_mul_f32 v[180:181], v[94:95], v[108:109] op_sel_hi:[1,0]
	v_pk_fma_f32 v[184:185], v[34:35], v[126:127], v[184:185]
	v_pk_mul_f32 v[182:183], v[96:97], v[108:109] op_sel_hi:[1,0]
	v_add_f32_e32 v169, v184, v185
	ds_read_b128 v[90:93], v84 offset:14208
	ds_read_b128 v[94:97], v84 offset:14464
	ds_read_b128 v[120:123], v84 offset:13536
	ds_read_b128 v[124:127], v84 offset:13792
	s_waitcnt lgkmcnt(6)
	v_pk_fma_f32 v[32:33], v[136:137], v[32:33], v[176:177] op_sel_hi:[0,1,1]
	v_pk_fma_f32 v[38:39], v[136:137], v[38:39], v[178:179] op_sel_hi:[0,1,1]
	v_pk_fma_f32 v[36:37], v[136:137], v[36:37], v[180:181] op_sel_hi:[0,1,1]
	v_pk_fma_f32 v[34:35], v[136:137], v[34:35], v[182:183] op_sel_hi:[0,1,1]
	v_mov_b32_e32 v142, v109
	v_pk_mul_f32 v[184:185], v[32:33], v[98:99]
	v_pk_mul_f32 v[176:177], v[112:113], v[142:143] op_sel_hi:[1,0]
	v_pk_fma_f32 v[184:185], v[38:39], v[100:101], v[184:185]
	v_pk_mul_f32 v[178:179], v[114:115], v[142:143] op_sel_hi:[1,0]
	v_pk_fma_f32 v[184:185], v[36:37], v[102:103], v[184:185]
	v_pk_mul_f32 v[180:181], v[116:117], v[142:143] op_sel_hi:[1,0]
	v_pk_fma_f32 v[184:185], v[34:35], v[104:105], v[184:185]
	v_pk_mul_f32 v[182:183], v[118:119], v[142:143] op_sel_hi:[1,0]
	v_add_f32_e32 v170, v184, v185
	ds_read_b128 v[112:115], v84 offset:15392
	ds_read_b128 v[116:119], v84 offset:15648
	ds_read_b128 v[98:101], v84 offset:14720
	ds_read_b128 v[102:105], v84 offset:14976
	s_waitcnt lgkmcnt(4)
	v_mov_b32_e32 v144, v137
	v_pk_fma_f32 v[32:33], v[144:145], v[32:33], v[176:177] op_sel_hi:[0,1,1]
	v_pk_fma_f32 v[38:39], v[144:145], v[38:39], v[178:179] op_sel_hi:[0,1,1]
	v_pk_fma_f32 v[36:37], v[144:145], v[36:37], v[180:181] op_sel_hi:[0,1,1]
	v_pk_fma_f32 v[34:35], v[144:145], v[34:35], v[182:183] op_sel_hi:[0,1,1]
	v_pk_mul_f32 v[184:185], v[32:33], v[120:121]
	v_pk_mul_f32 v[176:177], v[90:91], v[128:129] op_sel_hi:[1,0]
	v_pk_fma_f32 v[184:185], v[38:39], v[122:123], v[184:185]
	v_pk_mul_f32 v[178:179], v[92:93], v[128:129] op_sel_hi:[1,0]
	v_pk_fma_f32 v[184:185], v[36:37], v[124:125], v[184:185]
	v_pk_mul_f32 v[180:181], v[94:95], v[128:129] op_sel_hi:[1,0]
	v_pk_fma_f32 v[184:185], v[34:35], v[126:127], v[184:185]
	v_pk_mul_f32 v[182:183], v[96:97], v[128:129] op_sel_hi:[1,0]
	v_add_f32_e32 v171, v184, v185
	ds_read_b128 v[90:93], v84 offset:16576
	ds_read_b128 v[94:97], v84 offset:16832
	ds_read_b128 v[120:123], v84 offset:15904
	ds_read_b128 v[124:127], v84 offset:16160
	s_waitcnt lgkmcnt(4)
	v_pk_fma_f32 v[32:33], v[138:139], v[32:33], v[176:177] op_sel_hi:[0,1,1]
	v_pk_fma_f32 v[38:39], v[138:139], v[38:39], v[178:179] op_sel_hi:[0,1,1]
	v_pk_fma_f32 v[36:37], v[138:139], v[36:37], v[180:181] op_sel_hi:[0,1,1]
	v_pk_fma_f32 v[34:35], v[138:139], v[34:35], v[182:183] op_sel_hi:[0,1,1]
	v_mov_b32_e32 v142, v129
	v_pk_mul_f32 v[184:185], v[32:33], v[98:99]
	v_pk_mul_f32 v[176:177], v[112:113], v[142:143] op_sel_hi:[1,0]
	v_pk_fma_f32 v[184:185], v[38:39], v[100:101], v[184:185]
	v_pk_mul_f32 v[178:179], v[114:115], v[142:143] op_sel_hi:[1,0]
	v_pk_fma_f32 v[184:185], v[36:37], v[102:103], v[184:185]
	v_pk_mul_f32 v[180:181], v[116:117], v[142:143] op_sel_hi:[1,0]
	v_pk_fma_f32 v[184:185], v[34:35], v[104:105], v[184:185]
	v_pk_mul_f32 v[182:183], v[118:119], v[142:143] op_sel_hi:[1,0]
	v_add_f32_e32 v172, v184, v185
	ds_read_b128 v[112:115], v84 offset:17760
	ds_read_b128 v[116:119], v84 offset:18016
	ds_read_b128 v[98:101], v84 offset:17088
	ds_read_b128 v[102:105], v84 offset:17344
	s_waitcnt lgkmcnt(4)
; __device__ __forceinline__ bf16_t f2bf(float f) { return (bf16_t)(pack2(f, 0.f) & 0xffffu); }
; __device__ __forceinline__ int tidx() { int t = threadIdx.x & 255; asm volatile("" : "+v"(t)); return t; }
; __device__ __forceinline__ int half_id() { int t = (int)(threadIdx.x >> 8); asm volatile("" : "+v"(t)); return __builtin_amdgcn_readfirstlane(t); }
; #define LAS3 __attribute__((address_space(3)))
; __device__ __forceinline__ void half_barrier(char* smem_half) {
;   const int h = half_id();
;   LAS3 unsigned* cnt = (LAS3 unsigned*)(smem_half + (2 - h) * 65536 + 8 + h * 4);
;   asm volatile("s_waitcnt lgkmcnt(0)" ::: "memory");
;   if ((tidx() & 63) == 0) {
;     const unsigned old = __hip_atomic_fetch_add(cnt, 1u, __ATOMIC_RELAXED, __HIP_MEMORY_SCOPE_WORKGROUP);
;     const unsigned target = (old & ~3u) + 4u;
;     while (__hip_atomic_load(cnt, __ATOMIC_RELAXED, __HIP_MEMORY_SCOPE_WORKGROUP) < target) __builtin_amdgcn_s_sleep(1);
;   }
; __device__ __forceinline__ void ssd_scan_unit(CP p, int l, int u, char* smem) {
;     ...
;       hs[0] = fmaf(a, hs[0], xdt * B0.x); hs[1] = fmaf(a, hs[1], xdt * B0.y); hs[2] = fmaf(a, hs[2], xdt * B0.z); hs[3] = fmaf(a, hs[3], xdt * B0.w);
;       hs[4] = fmaf(a, hs[4], xdt * B1.x); hs[5] = fmaf(a, hs[5], xdt * B1.y); hs[6] = fmaf(a, hs[6], xdt * B1.z); hs[7] = fmaf(a, hs[7], xdt * B1.w);
;       float y = hs[0] * C0.x + hs[1] * C0.y + hs[2] * C0.z + hs[3] * C0.w + hs[4] * C1.x + hs[5] * C1.y + hs[6] * C1.z + hs[7] * C1.w;
;       y = allreduce16(y);
;       y = fmaf(Dh, xr, y);
;       if (j == s) ykeep = y;
;       B0 = B0n; B1 = B1n; C0 = C0n; C1 = C1n; xdt = xdtn; xr = xrn; a = an;
;     }
;     Y[(size_t)(rowof(b, c * 16) + j) * 1024 + h * 64 + q * 16 + prow] = f2bf(ykeep);
;     if (c + 1 < NCH) lwrite((c + 1) & 1);
;     half_barrier(smem);
	v_mov_b32_e32 v144, v139
	v_pk_fma_f32 v[32:33], v[144:145], v[32:33], v[176:177] op_sel_hi:[0,1,1]
	v_pk_fma_f32 v[38:39], v[144:145], v[38:39], v[178:179] op_sel_hi:[0,1,1]
	v_pk_fma_f32 v[36:37], v[144:145], v[36:37], v[180:181] op_sel_hi:[0,1,1]
	v_pk_fma_f32 v[34:35], v[144:145], v[34:35], v[182:183] op_sel_hi:[0,1,1]
	v_pk_mul_f32 v[184:185], v[32:33], v[120:121]
	v_pk_mul_f32 v[176:177], v[90:91], v[130:131] op_sel_hi:[1,0]
	v_pk_fma_f32 v[184:185], v[38:39], v[122:123], v[184:185]
	v_pk_mul_f32 v[178:179], v[92:93], v[130:131] op_sel_hi:[1,0]
	v_pk_fma_f32 v[184:185], v[36:37], v[124:125], v[184:185]
	v_pk_mul_f32 v[180:181], v[94:95], v[130:131] op_sel_hi:[1,0]
	v_pk_fma_f32 v[184:185], v[34:35], v[126:127], v[184:185]
	v_pk_mul_f32 v[182:183], v[96:97], v[130:131] op_sel_hi:[1,0]
	v_add_f32_e32 v173, v184, v185
	ds_read_b128 v[120:123], v84 offset:18272
	ds_read_b128 v[124:127], v84 offset:18528
	s_waitcnt lgkmcnt(2)
	v_pk_fma_f32 v[32:33], v[140:141], v[32:33], v[176:177] op_sel_hi:[0,1,1]
	v_pk_fma_f32 v[38:39], v[140:141], v[38:39], v[178:179] op_sel_hi:[0,1,1]
	v_pk_fma_f32 v[36:37], v[140:141], v[36:37], v[180:181] op_sel_hi:[0,1,1]
	v_pk_fma_f32 v[34:35], v[140:141], v[34:35], v[182:183] op_sel_hi:[0,1,1]
	v_mov_b32_e32 v142, v131
	v_pk_mul_f32 v[184:185], v[32:33], v[98:99]
	v_pk_mul_f32 v[176:177], v[112:113], v[142:143] op_sel_hi:[1,0]
	v_pk_fma_f32 v[184:185], v[38:39], v[100:101], v[184:185]
	v_pk_mul_f32 v[178:179], v[114:115], v[142:143] op_sel_hi:[1,0]
	v_pk_fma_f32 v[184:185], v[36:37], v[102:103], v[184:185]
	v_pk_mul_f32 v[180:181], v[116:117], v[142:143] op_sel_hi:[1,0]
	v_pk_fma_f32 v[184:185], v[34:35], v[104:105], v[184:185]
	v_pk_mul_f32 v[182:183], v[118:119], v[142:143] op_sel_hi:[1,0]
	v_add_f32_e32 v174, v184, v185
	s_waitcnt lgkmcnt(0)
	v_mov_b32_e32 v144, v141
	v_pk_fma_f32 v[32:33], v[144:145], v[32:33], v[176:177] op_sel_hi:[0,1,1]
	v_pk_fma_f32 v[38:39], v[144:145], v[38:39], v[178:179] op_sel_hi:[0,1,1]
	v_pk_fma_f32 v[36:37], v[144:145], v[36:37], v[180:181] op_sel_hi:[0,1,1]
	v_pk_fma_f32 v[34:35], v[144:145], v[34:35], v[182:183] op_sel_hi:[0,1,1]
	v_pk_mul_f32 v[184:185], v[32:33], v[120:121]
	v_pk_fma_f32 v[184:185], v[38:39], v[122:123], v[184:185]
	v_pk_fma_f32 v[184:185], v[36:37], v[124:125], v[184:185]
	v_pk_fma_f32 v[184:185], v[34:35], v[126:127], v[184:185]
	v_add_f32_e32 v175, v184, v185
	v_add_f32_dpp v160, v160, v160 row_ror:8 row_mask:0xf bank_mask:0x3 bound_ctrl:1
	v_add_f32_dpp v161, v161, v161 row_ror:8 row_mask:0xf bank_mask:0x3 bound_ctrl:1
	v_add_f32_dpp v162, v162, v162 row_ror:8 row_mask:0xf bank_mask:0x3 bound_ctrl:1
	v_add_f32_dpp v163, v163, v163 row_ror:8 row_mask:0xf bank_mask:0x3 bound_ctrl:1
	v_add_f32_dpp v164, v164, v164 row_ror:8 row_mask:0xf bank_mask:0x3 bound_ctrl:1
	v_add_f32_dpp v165, v165, v165 row_ror:8 row_mask:0xf bank_mask:0x3 bound_ctrl:1
	v_add_f32_dpp v166, v166, v166 row_ror:8 row_mask:0xf bank_mask:0x3 bound_ctrl:1
	v_add_f32_dpp v167, v167, v167 row_ror:8 row_mask:0xf bank_mask:0x3 bound_ctrl:1
	v_add_f32_dpp v160, v168, v168 row_ror:8 row_mask:0xf bank_mask:0xc bound_ctrl:1
	v_add_f32_dpp v161, v169, v169 row_ror:8 row_mask:0xf bank_mask:0xc bound_ctrl:1
	v_add_f32_dpp v162, v170, v170 row_ror:8 row_mask:0xf bank_mask:0xc bound_ctrl:1
	v_add_f32_dpp v163, v171, v171 row_ror:8 row_mask:0xf bank_mask:0xc bound_ctrl:1
	v_add_f32_dpp v164, v172, v172 row_ror:8 row_mask:0xf bank_mask:0xc bound_ctrl:1
	v_add_f32_dpp v165, v173, v173 row_ror:8 row_mask:0xf bank_mask:0xc bound_ctrl:1
	v_add_f32_dpp v166, v174, v174 row_ror:8 row_mask:0xf bank_mask:0xc bound_ctrl:1
	v_add_f32_dpp v167, v175, v175 row_ror:8 row_mask:0xf bank_mask:0xc bound_ctrl:1
	v_add_f32_dpp v160, v160, v160 row_half_mirror row_mask:0xf bank_mask:0x5 bound_ctrl:1
	v_add_f32_dpp v161, v161, v161 row_half_mirror row_mask:0xf bank_mask:0x5 bound_ctrl:1
	v_add_f32_dpp v162, v162, v162 row_half_mirror row_mask:0xf bank_mask:0x5 bound_ctrl:1
	v_add_f32_dpp v163, v163, v163 row_half_mirror row_mask:0xf bank_mask:0x5 bound_ctrl:1
	v_add_f32_dpp v160, v164, v164 row_half_mirror row_mask:0xf bank_mask:0xa bound_ctrl:1
	v_add_f32_dpp v161, v165, v165 row_half_mirror row_mask:0xf bank_mask:0xa bound_ctrl:1
	v_add_f32_dpp v162, v166, v166 row_half_mirror row_mask:0xf bank_mask:0xa bound_ctrl:1
	v_add_f32_dpp v163, v167, v167 row_half_mirror row_mask:0xf bank_mask:0xa bound_ctrl:1
	v_and_b32_e32 v188, 2, v44
	v_cmp_ne_u32_e32 vcc, 0, v188
	v_and_b32_e32 v188, 1, v44
	s_nop 0
	v_cndmask_b32_e32 v189, v160, v162, vcc
	v_cndmask_b32_e32 v190, v162, v160, vcc
	v_cndmask_b32_e32 v191, v161, v163, vcc
	v_cndmask_b32_e32 v192, v163, v161, vcc
	v_cmp_ne_u32_e32 vcc, 0, v188
	v_add_f32_dpp v160, v190, v189 quad_perm:[2,3,0,1] row_mask:0xf bank_mask:0xf bound_ctrl:1
	v_add_f32_dpp v161, v192, v191 quad_perm:[2,3,0,1] row_mask:0xf bank_mask:0xf bound_ctrl:1
	v_cndmask_b32_e32 v189, v160, v161, vcc
	v_cndmask_b32_e32 v190, v161, v160, vcc
	s_nop 1
	v_add_f32_dpp v187, v190, v189 quad_perm:[1,0,3,2] row_mask:0xf bank_mask:0xf bound_ctrl:1
	v_fma_f32 v60, v43, v186, v187
	s_lshl_b32 s5, s4, 4
	s_add_i32 s5, s5, s11
	s_cmp_eq_u32 s4, 0
	s_cselect_b32 s5, s10, s5
	v_or_b32_e32 v8, s5, v44
	v_ashrrev_i32_e32 v9, 31, v8
	v_lshlrev_b64 v[8:9], 11, v[8:9]
	v_cvt_pk_bf16_f32 v10, v60, s0
	v_lshl_add_u64 v[8:9], v[28:29], 0, v[8:9]
	global_store_short v[8:9], v10, off
	s_waitcnt lgkmcnt(0)
	s_mov_b64 s[12:13], exec
	s_mov_b64 exec, 1
	ds_add_u32 v193, v195 offset:8
	s_mov_b64 exec, s[12:13]
	v_add_u32_e32 v194, 4, v194
